# speedup vs baseline: 1.0086x; 1.0086x over previous
; __device__ __forceinline__ void gemm_run(const Params& p, const u16* A1, const u16* Bt1, int M1, int N1, int K, int mode1,
;                                          const float* resid, u16* shm, const u16* A2, const u16* Bt2, int M2, int N2,
;                                          int mode2) {
;     ...
;     const int nM = (second ? M2 : M1) / BM, nN = (second ? N2 : N1) / BM;
;     int nig = WGM * nN, gid = wgid / nig, fm = gid * WGM, gsz = min(nM - fm, WGM);
;     int pm = fm + ((wgid % nig) % gsz), pn = (wgid % nig) / gsz, brow = pm * BM, bcol = pn * BM;
;     bool swp = false;
;     if (mode == EPI_PROJ) swp = (pm >= 16 && pm < 24) || pm == 46 || pm == 47 || pm == 50 || pm == 51;
;     else if (mode == EPI_XKV) swp = pm >= 2;
;     if (swp) {
;       const u16* tA = A; A = Bt; Bt = tA;
;       const int tb = brow; brow = bcol; bcol = tb;
;       mode = mode == EPI_PROJ ? EPI_PROJ_T : EPI_XKV_T;
.LBB0_386:
	s_lshr_b32 s8, s8, 5
	s_and_b32 s8, s8, 0x1f8
	v_cvt_f32_u32_e32 v0, s8
	s_sub_i32 s12, 0, s8
	s_abs_i32 s11, s0
	s_ashr_i32 s9, s0, 31
	v_rcp_iflag_f32_e32 v0, v0
	s_nop 0
	v_mul_f32_e32 v0, 0x4f7ffffe, v0
	v_cvt_u32_f32_e32 v0, v0
	s_nop 0
	v_readfirstlane_b32 s13, v0
	s_mul_i32 s12, s12, s13
	s_mul_hi_u32 s12, s13, s12
	s_add_i32 s13, s13, s12
	s_mul_hi_u32 s12, s11, s13
	s_mul_i32 s13, s12, s8
	s_sub_i32 s11, s11, s13
	s_add_i32 s56, s12, 1
	s_sub_i32 s13, s11, s8
	s_cmp_ge_u32 s11, s8
	s_cselect_b32 s12, s56, s12
	s_cselect_b32 s11, s13, s11
	s_add_i32 s13, s12, 1
	s_cmp_ge_u32 s11, s8
	s_cselect_b32 s11, s13, s12
	s_xor_b32 s11, s11, s9
	s_sub_i32 s9, s11, s9
	s_lshl_b32 s12, s9, 3
	s_sub_i32 s1, s1, s12
	s_mul_i32 s9, s9, s8
	s_min_i32 s8, s1, 8
	v_cvt_f32_i32_e32 v0, s8
	s_sub_i32 s9, s0, s9
	s_sext_i32_i16 s0, s9
	v_cvt_f32_i32_e32 v2, s0
	v_rcp_iflag_f32_e32 v3, v0
	s_xor_b32 s0, s0, s8
	s_ashr_i32 s0, s0, 30
	s_or_b32 s11, s0, 1
	v_mul_f32_e32 v3, v2, v3
	v_trunc_f32_e32 v3, v3
	v_fma_f32 v2, -v3, v0, v2
	v_cvt_i32_f32_e32 v3, v3
	v_cmp_ge_f32_e64 s[0:1], |v2|, |v0|
	s_and_b64 s[0:1], s[0:1], exec
	s_cselect_b32 s0, s11, 0
	v_readfirstlane_b32 s11, v3
	s_add_i32 s11, s11, s0
	s_mul_i32 s0, s11, s8
	s_sub_i32 s0, s9, s0
	s_sext_i32_i16 s0, s0
	s_add_i32 s12, s12, s0
	s_and_b32 s0, s58, 7
	s_cmp_lg_u32 s0, 0
	s_cbranch_scc1 .Lnopm
	s_lshr_b32 s0, s58, 3
	s_and_b32 s13, s12, 7
	s_mul_i32 s13, s13, s0
	s_lshr_b32 s12, s12, 3
	s_add_i32 s12, s12, s13
.Lnopm:
	s_cmp_lg_u32 s10, 0
	s_cbranch_scc0 .LBB0_388
	s_cmp_eq_u32 s10, 1
	s_cselect_b64 s[0:1], -1, 0
	s_cmp_gt_i32 s12, 1
	s_cselect_b64 s[8:9], -1, 0
	s_and_b64 s[0:1], s[0:1], s[8:9]
	s_mov_b32 s90, 7
	s_cbranch_execz .LBB0_389
	s_branch .LBB0_393
